# v16: v15 + prologue SiLU(c) table: 20 loads issued up front with counted waits (was a 20-trip loop, one load + vmcnt(0) per trip)
# speedup vs baseline: 1.0011x; 1.0011x over previous
; __device__ __forceinline__ void p0_prologue(const Args& a, Frame& F) {
;     ...
;     for (int i = F.tid; i < 5 * D; i += NWAVES * 64) { const float v = (i < 4 * D) ? a.in[1][i] : a.in[3][i - 4 * D]; act[i] = v / (1.f + __expf(-v)); }
.LBB0_15:
	s_or_b64 exec, exec, s[0:1]
	s_cmp_lt_i32 s60, 1
	s_cselect_b64 s[0:1], -1, 0
	s_cmp_gt_i32 s61, 0
	v_writelane_b32 v254, s68, 8
	s_cselect_b64 s[4:5], -1, 0
	s_and_b64 s[0:1], s[0:1], s[4:5]
	v_writelane_b32 v254, s69, 9
	v_writelane_b32 v254, s70, 10
	s_andn2_b64 vcc, exec, s[0:1]
	v_writelane_b32 v254, s71, 11
	s_cbranch_vccnz .LBB0_104
	s_getreg_b32 s4, hwreg(HW_REG_HW_ID, 0, 6)
	s_lshl_b32 s4, s4, 2
	s_add_i32 s4, s4, 0
	s_add_i32 s4, s4, 0x20540
	v_mov_b32_e32 v0, s4
	ds_read_b32 v0, v0
	s_movk_i32 s4, 0x2800
	v_mbcnt_lo_u32_b32 v1, -1, 0
	v_mbcnt_hi_u32_b32 v1, -1, v1
	s_waitcnt lgkmcnt(0)
	v_readfirstlane_b32 s5, v0
	s_nop 1
	v_lshl_add_u32 v128, s5, 6, v1
	s_nop 0
	v_readfirstlane_b32 s24, v128
	v_cmp_gt_i32_e32 vcc, s4, v128
	s_and_saveexec_b64 s[4:5], vcc
	s_cbranch_execz .LBB0_19
	v_mov_b32_e32 v0, s10
	v_mov_b32_e32 v1, s11
	v_lshl_add_u32 v2, v128, 2, 0
	v_ashrrev_i32_e32 v129, 31, v128
	s_movk_i32 s10, 0x8000
	v_add_u32_e32 v4, 0x12000, v2
	v_lshl_add_u64 v[0:1], v[128:129], 2, v[0:1]
	s_mov_b64 s[6:7], 0
	s_movk_i32 s18, 0x2000
	v_mov_b32_e32 v3, 0
	s_mov_b32 s11, -1
	s_mov_b64 s[16:17], 0x800
	s_movk_i32 s19, 0x25ff
	v_mov_b32_e32 v2, v128
	v_lshl_add_u64 v[12:13], v[2:3], 2, s[14:15]
	s_mov_b64 s[16:17], 0x1000
	global_load_dword v16, v[0:1], off
	global_load_dword v17, v[0:1], off offset:2048
	v_lshl_add_u64 v[0:1], v[0:1], 0, s[16:17]
	global_load_dword v18, v[0:1], off
	global_load_dword v19, v[0:1], off offset:2048
	v_lshl_add_u64 v[0:1], v[0:1], 0, s[16:17]
	global_load_dword v20, v[0:1], off
	global_load_dword v21, v[0:1], off offset:2048
	v_lshl_add_u64 v[0:1], v[0:1], 0, s[16:17]
	global_load_dword v22, v[0:1], off
	global_load_dword v23, v[0:1], off offset:2048
	v_lshl_add_u64 v[0:1], v[0:1], 0, s[16:17]
	global_load_dword v24, v[0:1], off
	global_load_dword v25, v[0:1], off offset:2048
	v_lshl_add_u64 v[0:1], v[0:1], 0, s[16:17]
	global_load_dword v26, v[0:1], off
	global_load_dword v27, v[0:1], off offset:2048
	v_lshl_add_u64 v[0:1], v[0:1], 0, s[16:17]
	global_load_dword v28, v[0:1], off
	global_load_dword v29, v[0:1], off offset:2048
	v_lshl_add_u64 v[0:1], v[0:1], 0, s[16:17]
	global_load_dword v30, v[0:1], off
	global_load_dword v31, v[0:1], off offset:2048
	global_load_dword v32, v[12:13], off
	global_load_dword v33, v[12:13], off offset:2048
	v_lshl_add_u64 v[12:13], v[12:13], 0, s[16:17]
	global_load_dword v34, v[12:13], off
	global_load_dword v35, v[12:13], off offset:2048
	s_waitcnt vmcnt(19)
	v_mul_f32_e32 v6, 0xbfb8aa3b, v16
	v_exp_f32_e32 v6, v6
	s_nop 0
	v_add_f32_e32 v6, 1.0, v6
	v_div_scale_f32 v7, s[20:21], v6, v6, v16
	v_rcp_f32_e32 v8, v7
	v_div_scale_f32 v9, vcc, v16, v6, v16
	v_fma_f32 v10, -v7, v8, 1.0
	v_fmac_f32_e32 v8, v10, v8
	v_mul_f32_e32 v10, v9, v8
	v_fma_f32 v11, -v7, v10, v9
	v_fmac_f32_e32 v10, v11, v8
	v_fma_f32 v7, -v7, v10, v9
	v_div_fmas_f32 v7, v7, v8, v10
	v_div_fixup_f32 v5, v7, v6, v16
	ds_write_b32 v4, v5
	s_waitcnt vmcnt(18)
	v_mul_f32_e32 v6, 0xbfb8aa3b, v17
	v_exp_f32_e32 v6, v6
	s_nop 0
	v_add_f32_e32 v6, 1.0, v6
	v_div_scale_f32 v7, s[20:21], v6, v6, v17
	v_rcp_f32_e32 v8, v7
	v_div_scale_f32 v9, vcc, v17, v6, v17
	v_fma_f32 v10, -v7, v8, 1.0
	v_fmac_f32_e32 v8, v10, v8
	v_mul_f32_e32 v10, v9, v8
	v_fma_f32 v11, -v7, v10, v9
	v_fmac_f32_e32 v10, v11, v8
	v_fma_f32 v7, -v7, v10, v9
	v_div_fmas_f32 v7, v7, v8, v10
	v_div_fixup_f32 v5, v7, v6, v17
	ds_write_b32 v4, v5 offset:2048
	s_waitcnt vmcnt(17)
	v_mul_f32_e32 v6, 0xbfb8aa3b, v18
	v_exp_f32_e32 v6, v6
	s_nop 0
	v_add_f32_e32 v6, 1.0, v6
	v_div_scale_f32 v7, s[20:21], v6, v6, v18
	v_rcp_f32_e32 v8, v7
	v_div_scale_f32 v9, vcc, v18, v6, v18
	v_fma_f32 v10, -v7, v8, 1.0
	v_fmac_f32_e32 v8, v10, v8
	v_mul_f32_e32 v10, v9, v8
	v_fma_f32 v11, -v7, v10, v9
	v_fmac_f32_e32 v10, v11, v8
	v_fma_f32 v7, -v7, v10, v9
	v_div_fmas_f32 v7, v7, v8, v10
	v_div_fixup_f32 v5, v7, v6, v18
	ds_write_b32 v4, v5 offset:4096
	s_waitcnt vmcnt(16)
	v_mul_f32_e32 v6, 0xbfb8aa3b, v19
	v_exp_f32_e32 v6, v6
	s_nop 0
	v_add_f32_e32 v6, 1.0, v6
	v_div_scale_f32 v7, s[20:21], v6, v6, v19
	v_rcp_f32_e32 v8, v7
	v_div_scale_f32 v9, vcc, v19, v6, v19
	v_fma_f32 v10, -v7, v8, 1.0
	v_fmac_f32_e32 v8, v10, v8
	v_mul_f32_e32 v10, v9, v8
	v_fma_f32 v11, -v7, v10, v9
	v_fmac_f32_e32 v10, v11, v8
	v_fma_f32 v7, -v7, v10, v9
	v_div_fmas_f32 v7, v7, v8, v10
	v_div_fixup_f32 v5, v7, v6, v19
	ds_write_b32 v4, v5 offset:6144
	s_waitcnt vmcnt(15)
	v_mul_f32_e32 v6, 0xbfb8aa3b, v20
	v_exp_f32_e32 v6, v6
	s_nop 0
	v_add_f32_e32 v6, 1.0, v6
	v_div_scale_f32 v7, s[20:21], v6, v6, v20
	v_rcp_f32_e32 v8, v7
	v_div_scale_f32 v9, vcc, v20, v6, v20
	v_fma_f32 v10, -v7, v8, 1.0
	v_fmac_f32_e32 v8, v10, v8
	v_mul_f32_e32 v10, v9, v8
	v_fma_f32 v11, -v7, v10, v9
	v_fmac_f32_e32 v10, v11, v8
	v_fma_f32 v7, -v7, v10, v9
	v_div_fmas_f32 v7, v7, v8, v10
	v_div_fixup_f32 v5, v7, v6, v20
	ds_write_b32 v4, v5 offset:8192
	s_waitcnt vmcnt(14)
	v_mul_f32_e32 v6, 0xbfb8aa3b, v21
	v_exp_f32_e32 v6, v6
	s_nop 0
	v_add_f32_e32 v6, 1.0, v6
	v_div_scale_f32 v7, s[20:21], v6, v6, v21
	v_rcp_f32_e32 v8, v7
	v_div_scale_f32 v9, vcc, v21, v6, v21
	v_fma_f32 v10, -v7, v8, 1.0
	v_fmac_f32_e32 v8, v10, v8
	v_mul_f32_e32 v10, v9, v8
	v_fma_f32 v11, -v7, v10, v9
	v_fmac_f32_e32 v10, v11, v8
	v_fma_f32 v7, -v7, v10, v9
	v_div_fmas_f32 v7, v7, v8, v10
	v_div_fixup_f32 v5, v7, v6, v21
	ds_write_b32 v4, v5 offset:10240
	s_waitcnt vmcnt(13)
	v_mul_f32_e32 v6, 0xbfb8aa3b, v22
	v_exp_f32_e32 v6, v6
	s_nop 0
	v_add_f32_e32 v6, 1.0, v6
	v_div_scale_f32 v7, s[20:21], v6, v6, v22
	v_rcp_f32_e32 v8, v7
	v_div_scale_f32 v9, vcc, v22, v6, v22
	v_fma_f32 v10, -v7, v8, 1.0
	v_fmac_f32_e32 v8, v10, v8
	v_mul_f32_e32 v10, v9, v8
	v_fma_f32 v11, -v7, v10, v9
	v_fmac_f32_e32 v10, v11, v8
	v_fma_f32 v7, -v7, v10, v9
	v_div_fmas_f32 v7, v7, v8, v10
	v_div_fixup_f32 v5, v7, v6, v22
	ds_write_b32 v4, v5 offset:12288
	s_waitcnt vmcnt(12)
; __device__ __forceinline__ void p0_prologue(const Args& a, Frame& F) {
;     ...
;     for (int i = F.tid; i < 5 * D; i += NWAVES * 64) { const float v = (i < 4 * D) ? a.in[1][i] : a.in[3][i - 4 * D]; act[i] = v / (1.f + __expf(-v)); }
	v_mul_f32_e32 v6, 0xbfb8aa3b, v23
	v_exp_f32_e32 v6, v6
	s_nop 0
	v_add_f32_e32 v6, 1.0, v6
	v_div_scale_f32 v7, s[20:21], v6, v6, v23
	v_rcp_f32_e32 v8, v7
	v_div_scale_f32 v9, vcc, v23, v6, v23
	v_fma_f32 v10, -v7, v8, 1.0
	v_fmac_f32_e32 v8, v10, v8
	v_mul_f32_e32 v10, v9, v8
	v_fma_f32 v11, -v7, v10, v9
	v_fmac_f32_e32 v10, v11, v8
	v_fma_f32 v7, -v7, v10, v9
	v_div_fmas_f32 v7, v7, v8, v10
	v_div_fixup_f32 v5, v7, v6, v23
	ds_write_b32 v4, v5 offset:14336
	s_waitcnt vmcnt(11)
	v_mul_f32_e32 v6, 0xbfb8aa3b, v24
	v_exp_f32_e32 v6, v6
	s_nop 0
	v_add_f32_e32 v6, 1.0, v6
	v_div_scale_f32 v7, s[20:21], v6, v6, v24
	v_rcp_f32_e32 v8, v7
	v_div_scale_f32 v9, vcc, v24, v6, v24
	v_fma_f32 v10, -v7, v8, 1.0
	v_fmac_f32_e32 v8, v10, v8
	v_mul_f32_e32 v10, v9, v8
	v_fma_f32 v11, -v7, v10, v9
	v_fmac_f32_e32 v10, v11, v8
	v_fma_f32 v7, -v7, v10, v9
	v_div_fmas_f32 v7, v7, v8, v10
	v_div_fixup_f32 v5, v7, v6, v24
	ds_write_b32 v4, v5 offset:16384
	s_waitcnt vmcnt(10)
	v_mul_f32_e32 v6, 0xbfb8aa3b, v25
	v_exp_f32_e32 v6, v6
	s_nop 0
	v_add_f32_e32 v6, 1.0, v6
	v_div_scale_f32 v7, s[20:21], v6, v6, v25
	v_rcp_f32_e32 v8, v7
	v_div_scale_f32 v9, vcc, v25, v6, v25
	v_fma_f32 v10, -v7, v8, 1.0
	v_fmac_f32_e32 v8, v10, v8
	v_mul_f32_e32 v10, v9, v8
	v_fma_f32 v11, -v7, v10, v9
	v_fmac_f32_e32 v10, v11, v8
	v_fma_f32 v7, -v7, v10, v9
	v_div_fmas_f32 v7, v7, v8, v10
	v_div_fixup_f32 v5, v7, v6, v25
	ds_write_b32 v4, v5 offset:18432
	s_waitcnt vmcnt(9)
	v_mul_f32_e32 v6, 0xbfb8aa3b, v26
	v_exp_f32_e32 v6, v6
	s_nop 0
	v_add_f32_e32 v6, 1.0, v6
	v_div_scale_f32 v7, s[20:21], v6, v6, v26
	v_rcp_f32_e32 v8, v7
	v_div_scale_f32 v9, vcc, v26, v6, v26
	v_fma_f32 v10, -v7, v8, 1.0
	v_fmac_f32_e32 v8, v10, v8
	v_mul_f32_e32 v10, v9, v8
	v_fma_f32 v11, -v7, v10, v9
	v_fmac_f32_e32 v10, v11, v8
	v_fma_f32 v7, -v7, v10, v9
	v_div_fmas_f32 v7, v7, v8, v10
	v_div_fixup_f32 v5, v7, v6, v26
	ds_write_b32 v4, v5 offset:20480
	s_waitcnt vmcnt(8)
	v_mul_f32_e32 v6, 0xbfb8aa3b, v27
	v_exp_f32_e32 v6, v6
	s_nop 0
	v_add_f32_e32 v6, 1.0, v6
	v_div_scale_f32 v7, s[20:21], v6, v6, v27
	v_rcp_f32_e32 v8, v7
	v_div_scale_f32 v9, vcc, v27, v6, v27
	v_fma_f32 v10, -v7, v8, 1.0
	v_fmac_f32_e32 v8, v10, v8
	v_mul_f32_e32 v10, v9, v8
	v_fma_f32 v11, -v7, v10, v9
	v_fmac_f32_e32 v10, v11, v8
	v_fma_f32 v7, -v7, v10, v9
	v_div_fmas_f32 v7, v7, v8, v10
	v_div_fixup_f32 v5, v7, v6, v27
	ds_write_b32 v4, v5 offset:22528
	s_waitcnt vmcnt(7)
	v_mul_f32_e32 v6, 0xbfb8aa3b, v28
	v_exp_f32_e32 v6, v6
	s_nop 0
	v_add_f32_e32 v6, 1.0, v6
	v_div_scale_f32 v7, s[20:21], v6, v6, v28
	v_rcp_f32_e32 v8, v7
	v_div_scale_f32 v9, vcc, v28, v6, v28
	v_fma_f32 v10, -v7, v8, 1.0
	v_fmac_f32_e32 v8, v10, v8
	v_mul_f32_e32 v10, v9, v8
	v_fma_f32 v11, -v7, v10, v9
	v_fmac_f32_e32 v10, v11, v8
	v_fma_f32 v7, -v7, v10, v9
	v_div_fmas_f32 v7, v7, v8, v10
	v_div_fixup_f32 v5, v7, v6, v28
	ds_write_b32 v4, v5 offset:24576
	s_waitcnt vmcnt(6)
	v_mul_f32_e32 v6, 0xbfb8aa3b, v29
	v_exp_f32_e32 v6, v6
	s_nop 0
	v_add_f32_e32 v6, 1.0, v6
	v_div_scale_f32 v7, s[20:21], v6, v6, v29
	v_rcp_f32_e32 v8, v7
	v_div_scale_f32 v9, vcc, v29, v6, v29
	v_fma_f32 v10, -v7, v8, 1.0
	v_fmac_f32_e32 v8, v10, v8
	v_mul_f32_e32 v10, v9, v8
	v_fma_f32 v11, -v7, v10, v9
	v_fmac_f32_e32 v10, v11, v8
	v_fma_f32 v7, -v7, v10, v9
	v_div_fmas_f32 v7, v7, v8, v10
	v_div_fixup_f32 v5, v7, v6, v29
	ds_write_b32 v4, v5 offset:26624
	s_waitcnt vmcnt(5)
	v_mul_f32_e32 v6, 0xbfb8aa3b, v30
	v_exp_f32_e32 v6, v6
	s_nop 0
	v_add_f32_e32 v6, 1.0, v6
	v_div_scale_f32 v7, s[20:21], v6, v6, v30
	v_rcp_f32_e32 v8, v7
	v_div_scale_f32 v9, vcc, v30, v6, v30
	v_fma_f32 v10, -v7, v8, 1.0
	v_fmac_f32_e32 v8, v10, v8
	v_mul_f32_e32 v10, v9, v8
	v_fma_f32 v11, -v7, v10, v9
	v_fmac_f32_e32 v10, v11, v8
	v_fma_f32 v7, -v7, v10, v9
	v_div_fmas_f32 v7, v7, v8, v10
	v_div_fixup_f32 v5, v7, v6, v30
	ds_write_b32 v4, v5 offset:28672
	s_waitcnt vmcnt(4)
	v_mul_f32_e32 v6, 0xbfb8aa3b, v31
	v_exp_f32_e32 v6, v6
	s_nop 0
	v_add_f32_e32 v6, 1.0, v6
	v_div_scale_f32 v7, s[20:21], v6, v6, v31
	v_rcp_f32_e32 v8, v7
	v_div_scale_f32 v9, vcc, v31, v6, v31
	v_fma_f32 v10, -v7, v8, 1.0
	v_fmac_f32_e32 v8, v10, v8
	v_mul_f32_e32 v10, v9, v8
	v_fma_f32 v11, -v7, v10, v9
	v_fmac_f32_e32 v10, v11, v8
	v_fma_f32 v7, -v7, v10, v9
	v_div_fmas_f32 v7, v7, v8, v10
	v_div_fixup_f32 v5, v7, v6, v31
	ds_write_b32 v4, v5 offset:30720
	s_waitcnt vmcnt(3)
	v_mul_f32_e32 v6, 0xbfb8aa3b, v32
	v_exp_f32_e32 v6, v6
	s_nop 0
	v_add_f32_e32 v6, 1.0, v6
	v_div_scale_f32 v7, s[20:21], v6, v6, v32
	v_rcp_f32_e32 v8, v7
	v_div_scale_f32 v9, vcc, v32, v6, v32
	v_fma_f32 v10, -v7, v8, 1.0
	v_fmac_f32_e32 v8, v10, v8
	v_mul_f32_e32 v10, v9, v8
	v_fma_f32 v11, -v7, v10, v9
	v_fmac_f32_e32 v10, v11, v8
	v_fma_f32 v7, -v7, v10, v9
	v_div_fmas_f32 v7, v7, v8, v10
	v_div_fixup_f32 v5, v7, v6, v32
	ds_write_b32 v4, v5 offset:32768
	s_waitcnt vmcnt(2)
	v_mul_f32_e32 v6, 0xbfb8aa3b, v33
	v_exp_f32_e32 v6, v6
	s_nop 0
	v_add_f32_e32 v6, 1.0, v6
	v_div_scale_f32 v7, s[20:21], v6, v6, v33
	v_rcp_f32_e32 v8, v7
	v_div_scale_f32 v9, vcc, v33, v6, v33
	v_fma_f32 v10, -v7, v8, 1.0
	v_fmac_f32_e32 v8, v10, v8
	v_mul_f32_e32 v10, v9, v8
	v_fma_f32 v11, -v7, v10, v9
	v_fmac_f32_e32 v10, v11, v8
	v_fma_f32 v7, -v7, v10, v9
	v_div_fmas_f32 v7, v7, v8, v10
	v_div_fixup_f32 v5, v7, v6, v33
	ds_write_b32 v4, v5 offset:34816
	s_waitcnt vmcnt(1)
	v_mul_f32_e32 v6, 0xbfb8aa3b, v34
	v_exp_f32_e32 v6, v6
	s_nop 0
	v_add_f32_e32 v6, 1.0, v6
	v_div_scale_f32 v7, s[20:21], v6, v6, v34
	v_rcp_f32_e32 v8, v7
	v_div_scale_f32 v9, vcc, v34, v6, v34
	v_fma_f32 v10, -v7, v8, 1.0
	v_fmac_f32_e32 v8, v10, v8
	v_mul_f32_e32 v10, v9, v8
	v_fma_f32 v11, -v7, v10, v9
	v_fmac_f32_e32 v10, v11, v8
	v_fma_f32 v7, -v7, v10, v9
	v_div_fmas_f32 v7, v7, v8, v10
	v_div_fixup_f32 v5, v7, v6, v34
	ds_write_b32 v4, v5 offset:36864
	s_waitcnt vmcnt(0)
	v_mul_f32_e32 v6, 0xbfb8aa3b, v35
	v_exp_f32_e32 v6, v6
	s_nop 0
	v_add_f32_e32 v6, 1.0, v6
	v_div_scale_f32 v7, s[20:21], v6, v6, v35
	v_rcp_f32_e32 v8, v7
	v_div_scale_f32 v9, vcc, v35, v6, v35
	v_fma_f32 v10, -v7, v8, 1.0
	v_fmac_f32_e32 v8, v10, v8
	v_mul_f32_e32 v10, v9, v8
	v_fma_f32 v11, -v7, v10, v9
	v_fmac_f32_e32 v10, v11, v8
	v_fma_f32 v7, -v7, v10, v9
	v_div_fmas_f32 v7, v7, v8, v10
	v_div_fixup_f32 v5, v7, v6, v35
	ds_write_b32 v4, v5 offset:38912
	v_add_u32_e32 v2, 0x2800, v2
	v_add_u32_e32 v4, 0xa000, v4
	s_mov_b64 s[16:17], 0x3000
	v_lshl_add_u64 v[0:1], v[0:1], 0, s[16:17]
	s_mov_b64 s[16:17], 0x800
	s_mov_b64 s[6:7], exec
